# stack v71 + hgrn pass-0 item: all 128 rows' operand segments touched once at item start (4 dword loads per wave, junk destination) so the per-step gathers hit L2
# speedup vs baseline: 1.0072x; 1.0012x over previous
; __device__ __forceinline__ float fexp(float x) { return __builtin_amdgcn_exp2f(x * LOG2E); }
; #define HG_LOAD(n_) do { const size_t T0_ = (size_t)b * SEQ + seg * 128 + (n_) * 16; \
;         _Pragma("unroll") for (int j = 0; j < 4; ++j) { const bf16_t* zp = p.z + (T0_ + fq * 4 + j) * ZLD; qn[j] = zp[768 + kch]; fn[j] = zp[1024 + kch]; vn[j] = zp[1280 + kch]; } } while (0)
; __device__ __forceinline__ void hgrn_item(const Params& p, int l, int item, int pass, LAS unsigned char* lds) {
;     ...
;     const int kch = head * 64 + wv * 16 + fr;
;     const float lbv = p.lbs[l * 256 + kch];
;     const size_t iseg = ((size_t)b * 4 + head) * 16;
;     f32x4 S[4];
; #pragma unroll
;     for (int kt = 0; kt < 4; ++kt) S[kt] = ZERO4;
;     float segb = 0.f;
;     float ng[4] = {0.f, 0.f, 0.f, 0.f};
;     if (pass == 1) {
;         for (int s = 0; s < seg; ++s) { const float* Sp = p.hgS + (iseg + s) * 4096 + wv * 16 + fr; const float* Dp = p.hgD + (iseg + s) * 64;
; #pragma unroll
;             for (int kt = 0; kt < 4; ++kt) { const f32x4 dl = *(const f32x4*)(Dp + kt * 16 + fq * 4);
; #pragma unroll
;                 for (int j = 0; j < 4; ++j) S[kt][j] = fexp(dl[j]) * S[kt][j] + Sp[(kt * 16 + fq * 4 + j) * 64]; } }
; #pragma unroll
;         for (int j = 0; j < 4; ++j) ng[j] = p.hg_norm_g[l * 256 + head * 64 + wv * 16 + fq * 4 + j];
;     }
;     unsigned qn[4], fn[4], vn[4];
;     ...
;     HG_LOAD(0);
.LBB0_416:
	s_waitcnt vmcnt(7)
	v_mov_b32_e32 v14, v202
	s_lshr_b32 s0, s2, 6
	v_lshrrev_b32_e32 v3, 2, v14
	s_waitcnt vmcnt(4)
	v_and_b32_e32 v24, 15, v14
	v_ashrrev_i32_e32 v15, 8, v14
	s_and_b32 s0, s0, 2
	v_and_b32_e32 v25, 48, v3
	v_add_u32_e32 v20, s0, v15
	v_or_b32_e32 v16, v25, v24
	s_ashr_i32 s26, s69, 5
	v_lshl_or_b32 v4, v20, 6, v16
	v_add_u32_e32 v6, s40, v4
	s_bfe_u32 s0, s2, 0x40003
	s_ashr_i32 s27, s26, 31
	v_mov_b32_e32 v0, s23
	v_mov_b32_e32 v1, s97
	v_ashrrev_i32_e32 v7, 31, v6
	v_bfe_u32 v26, v14, 4, 2
	s_lshl_b64 s[4:5], s[26:27], 11
	s_lshl_b32 s6, s0, 7
	v_ashrrev_i32_e32 v5, 31, v4
	v_lshl_add_u64 v[0:1], v[6:7], 2, v[0:1]
	v_lshlrev_b32_e32 v3, 2, v26
	s_or_b32 s4, s4, s6
	v_lshlrev_b64 v[4:5], 1, v[4:5]
	global_load_dword v35, v[0:1], off
	v_lshl_add_u64 v[0:1], s[8:9], 0, v[4:5]
	v_or_b32_e32 v6, s4, v3
	s_movk_i32 s10, 0x1600
	v_or_b32_e32 v27, 1, v3
	v_or_b32_e32 v28, 2, v3
	v_or_b32_e32 v29, 3, v3
	v_mad_u64_u32 v[6:7], s[6:7], v6, s10, v[0:1]
	v_or_b32_e32 v8, s4, v27
	v_or_b32_e32 v10, s4, v28
	v_or_b32_e32 v3, s4, v29
	v_mad_i32_i24 v7, s5, v210, v7
	v_mad_u64_u32 v[8:9], s[6:7], v8, s10, v[0:1]
	v_mad_u64_u32 v[10:11], s[6:7], v10, s10, v[0:1]
	v_mad_u64_u32 v[12:13], s[6:7], v3, s10, v[0:1]
	v_mad_i32_i24 v9, s5, v210, v9
	v_mad_i32_i24 v11, s5, v210, v11
	v_mad_i32_i24 v13, s5, v210, v13
	v_add_u32_e32 v100, s4, v207
	v_mad_u64_u32 v[100:101], s[98:99], v100, s10, v[0:1]
	v_mad_i32_i24 v101, s5, v210, v101
	global_load_ushort v52, v[6:7], off offset:2048
	global_load_ushort v0, v[6:7], off offset:2560
	global_load_ushort v53, v[8:9], off offset:2048
	global_load_ushort v3, v[8:9], off offset:2560
	global_load_ushort v48, v[10:11], off offset:2048
	global_load_ushort v1, v[10:11], off offset:2560
	global_load_ushort v49, v[12:13], off offset:2048
	global_load_ushort v41, v[12:13], off offset:2560
	global_load_dword v99, v[100:101], off offset:2048
	global_load_dword v99, v[100:101], off offset:2560
	s_mov_b64 s[98:99], 0x58000
	v_lshl_add_u64 v[100:101], v[100:101], 0, s[98:99]
	global_load_dword v99, v[100:101], off offset:2048
	global_load_dword v99, v[100:101], off offset:2560
	v_and_b32_e32 v6, 64, v207
	s_mul_i32 s10, s26, 0xb00000
	s_mul_i32 s14, s0, 0xb0000
	v_and_b32_e32 v7, 63, v14
	s_mul_hi_i32 s11, s26, 0xb00000
	v_add_u32_e32 v8, 48, v14
	v_add_u32_e32 v9, 16, v14
	v_or_b32_e32 v11, v6, v7
	v_cmp_gt_u32_e64 s[4:5], 16, v7
	v_cmp_lt_u32_e64 s[6:7], 31, v7
	v_or_b32_e32 v7, 48, v24
	s_add_u32 s10, s10, s14
	v_and_or_b32 v8, v8, 63, v6
	v_and_or_b32 v9, v9, 63, v6
	v_or_b32_e32 v6, v6, v7
	s_addc_u32 s11, s11, 0
	v_lshlrev_b32_e32 v37, 2, v9
	v_lshlrev_b32_e32 v9, 5, v7
	v_lshlrev_b32_e32 v36, 2, v6
	v_mov_b64_e32 v[6:7], s[10:11]
	s_movk_i32 s10, 0x5800
	v_lshl_add_u32 v10, v15, 13, 0
	v_lshlrev_b32_e32 v42, 3, v26
	v_mad_u64_u32 v[6:7], s[10:11], v26, s10, v[6:7]
	v_lshlrev_b32_e32 v12, 5, v24
	v_lshlrev_b32_e32 v38, 2, v8
	v_lshlrev_b32_e32 v8, 2, v11
	v_add_u32_e32 v43, v10, v42
	v_lshl_add_u32 v21, v16, 5, v10
	v_lshl_add_u64 v[4:5], v[6:7], 0, v[4:5]
	v_mov_b32_e32 v30, 0
	v_cmp_eq_u32_e32 vcc, 3, v26
	v_xor_b32_e32 v39, 0x80, v8
	v_mul_i32_i24_e32 v33, 0xffffffe4, v16
	v_add_u32_e32 v34, v21, v42
	v_lshl_add_u64 v[22:23], s[8:9], 0, v[4:5]
	s_mov_b64 s[28:29], 0
	v_add_u32_e32 v32, v43, v12
	v_add_u32_e32 v31, v43, v9
	v_mov_b32_e32 v4, 0
	v_mov_b32_e32 v5, v30
	v_mov_b32_e32 v6, v30
	v_mov_b32_e32 v7, v30
	v_mov_b32_e32 v16, 0
	v_mov_b32_e32 v17, v30
	v_mov_b32_e32 v18, v30
	v_mov_b32_e32 v19, v30
	v_mov_b32_e32 v12, 0
	v_mov_b32_e32 v13, v30
	v_mov_b32_e32 v14, v30
	v_mov_b32_e32 v15, v30
	v_mov_b32_e32 v8, 0
	v_mov_b32_e32 v9, v30
	v_mov_b32_e32 v10, v30
	v_mov_b32_e32 v11, v30
	s_mov_b32 s14, 0x1a000
	s_waitcnt vmcnt(12)
	v_sub_f32_e32 v40, 1.0, v35
	s_mov_b32 s15, 0x17000
	s_mov_b32 s16, 0x19000
